# attention: K/V LDS staging fast path without the zero-select copies when the unit is not at a sequence start (48-66 VALU fewer per unit)
# baseline (speedup 1.0000x reference)
; #define LAS __attribute__((address_space(3)))
; __device__ __forceinline__ void attn_phase(LAS unsigned char* lds, const bf16_t* qp, const bf16_t* kvp, bf16_t* obuf, float* lse, const float* biasG, const int gi, const int rsh, const int G) {
;     ...
;         if (tid < 192) ((LAS float*)(lds + A_BT))[tid] = bn;
;         const int wbase = j == 0 ? 0 : ((2 * j + 1) % 3) * 128;
; #pragma unroll
;         for (int it = 0; it < 6; ++it) {
;             const int idx = tid + 512 * it, kl = idx >> 3, ch = idx & 7;
;             if (j == 0 || it < 4) {
;                 int row = wbase + kl; row = row >= 384 ? row - 384 : row;
;                 const bool pre = (np == 0) && (j == 0) && (kl < 128);
;                 const u32x4 z4 = (u32x4){0u, 0u, 0u, 0u};
;                 *(LAS u32x4*)(lds + A_K0 + ch * KCS + row * 16) = pre ? z4 : kr[it];
;                 *(LAS u32x4*)(lds + A_V0 + (ch >> 2) * VHS + row * 64 + (ch & 3) * 16) = pre ? z4 : vr[it];
;             }
;         }
.LBB0_104:
	s_cmp_eq_u32 s2, 0
	v_add_u32_e32 v0, s4, v97
	s_movk_i32 s23, 0x17f
	v_readlane_b32 s18, v255, 33
	s_cselect_b64 s[46:47], -1, 0
	s_cbranch_scc1 .Lat_slow
	v_add_u32_e32 v0, s4, v97
	v_add_u32_e32 v1, 0xfffffe80, v0
	v_cmp_lt_i32_e32 vcc, s23, v0
	s_nop 0
	v_cndmask_b32_e32 v8, v0, v1, vcc
	v_lshl_add_u32 v9, v8, 4, v239
	v_lshl_add_u32 v0, v8, 6, v240
	s_waitcnt vmcnt(4)
	ds_write_b128 v9, v[98:101]
	ds_write_b128 v0, v[102:105] offset:49280
	v_add_u32_e32 v0, s4, v180
	v_add_u32_e32 v1, 0xfffffe80, v0
	v_cmp_lt_i32_e32 vcc, s23, v0
	s_nop 0
	v_cndmask_b32_e32 v8, v0, v1, vcc
	v_lshl_add_u32 v9, v8, 4, v239
	v_lshl_add_u32 v0, v8, 6, v240
	ds_write_b128 v9, v[106:109]
	ds_write_b128 v0, v[110:113] offset:49280
	v_add_u32_e32 v0, s4, v234
	v_add_u32_e32 v1, 0xfffffe80, v0
	v_cmp_lt_i32_e32 vcc, s23, v0
	s_nop 0
	v_cndmask_b32_e32 v8, v0, v1, vcc
	v_lshl_add_u32 v9, v8, 4, v239
	v_lshl_add_u32 v0, v8, 6, v240
	ds_write_b128 v9, v[114:117]
	ds_write_b128 v0, v[126:129] offset:49280
	v_add_u32_e32 v0, s4, v235
	v_add_u32_e32 v1, 0xfffffe80, v0
	v_cmp_lt_i32_e32 vcc, s23, v0
	s_nop 0
	v_cndmask_b32_e32 v8, v0, v1, vcc
	v_lshl_add_u32 v9, v8, 4, v239
	v_lshl_add_u32 v0, v8, 6, v240
	ds_write_b128 v9, v[138:141]
	ds_write_b128 v0, v[142:145] offset:49280
	v_mov_b32_e32 v225, 0x1fcf
	s_andn2_b64 vcc, exec, s[24:25]
	s_cbranch_vccnz .LBB0_106
	v_add_u32_e32 v0, s4, v236
	v_add_u32_e32 v1, 0xfffffe80, v0
	v_cmp_lt_i32_e32 vcc, s23, v0
	s_nop 0
	v_cndmask_b32_e32 v8, v0, v1, vcc
	v_lshl_add_u32 v9, v8, 4, v239
	v_lshl_add_u32 v0, v8, 6, v240
	ds_write_b128 v9, v[118:121]
	ds_write_b128 v0, v[122:125] offset:49280
	v_add_u32_e32 v0, s4, v237
	v_add_u32_e32 v1, 0xfffffe80, v0
	v_cmp_lt_i32_e32 vcc, s23, v0
	s_nop 0
	v_cndmask_b32_e32 v8, v0, v1, vcc
	v_lshl_add_u32 v9, v8, 4, v239
	v_lshl_add_u32 v0, v8, 6, v240
	ds_write_b128 v9, v[130:133]
	ds_write_b128 v0, v[134:137] offset:49280
	s_branch .LBB0_106
.Lat_slow:
	v_add_u32_e32 v1, 0xfffffe80, v0
	v_cmp_lt_i32_e32 vcc, s23, v0
	v_readlane_b32 s19, v255, 34
	s_and_b64 s[18:19], s[18:19], s[46:47]
	v_cndmask_b32_e32 v8, v0, v1, vcc
	s_waitcnt vmcnt(4)
	v_cndmask_b32_e64 v3, v101, 0, s[18:19]
	v_cndmask_b32_e64 v2, v100, 0, s[18:19]
	v_cndmask_b32_e64 v1, v99, 0, s[18:19]
	v_cndmask_b32_e64 v0, v98, 0, s[18:19]
	v_lshl_add_u32 v9, v8, 4, v239
	s_waitcnt vmcnt(10)
	v_cndmask_b32_e64 v7, v105, 0, s[18:19]
	v_cndmask_b32_e64 v6, v104, 0, s[18:19]
	v_cndmask_b32_e64 v5, v103, 0, s[18:19]
	v_cndmask_b32_e64 v4, v102, 0, s[18:19]
	ds_write_b128 v9, v[0:3]
	v_lshl_add_u32 v0, v8, 6, v240
	ds_write_b128 v0, v[4:7] offset:49280
	v_add_u32_e32 v0, s4, v180
	v_readlane_b32 s18, v255, 29
	v_add_u32_e32 v1, 0xfffffe80, v0
	v_cmp_lt_i32_e32 vcc, s23, v0
	v_readlane_b32 s19, v255, 30
	s_and_b64 s[18:19], s[18:19], s[46:47]
	v_cndmask_b32_e32 v8, v0, v1, vcc
	s_waitcnt vmcnt(9)
	v_cndmask_b32_e64 v3, v109, 0, s[18:19]
	v_cndmask_b32_e64 v2, v108, 0, s[18:19]
	v_cndmask_b32_e64 v1, v107, 0, s[18:19]
	v_cndmask_b32_e64 v0, v106, 0, s[18:19]
	v_lshl_add_u32 v9, v8, 4, v239
	s_waitcnt vmcnt(8)
	v_cndmask_b32_e64 v7, v113, 0, s[18:19]
	v_cndmask_b32_e64 v6, v112, 0, s[18:19]
	v_cndmask_b32_e64 v5, v111, 0, s[18:19]
	v_cndmask_b32_e64 v4, v110, 0, s[18:19]
	ds_write_b128 v9, v[0:3]
	v_lshl_add_u32 v0, v8, 6, v240
	ds_write_b128 v0, v[4:7] offset:49280
	v_add_u32_e32 v0, s4, v234
	v_readlane_b32 s18, v255, 19
	v_add_u32_e32 v1, 0xfffffe80, v0
	v_cmp_lt_i32_e32 vcc, s23, v0
	v_readlane_b32 s19, v255, 20
	s_and_b64 s[18:19], s[18:19], s[46:47]
	v_cndmask_b32_e32 v8, v0, v1, vcc
	s_waitcnt vmcnt(7)
	v_cndmask_b32_e64 v3, v117, 0, s[18:19]
	v_cndmask_b32_e64 v2, v116, 0, s[18:19]
	v_cndmask_b32_e64 v1, v115, 0, s[18:19]
	v_cndmask_b32_e64 v0, v114, 0, s[18:19]
	v_lshl_add_u32 v9, v8, 4, v239
	s_waitcnt vmcnt(6)
	v_cndmask_b32_e64 v7, v129, 0, s[18:19]
	v_cndmask_b32_e64 v6, v128, 0, s[18:19]
	v_cndmask_b32_e64 v5, v127, 0, s[18:19]
	v_cndmask_b32_e64 v4, v126, 0, s[18:19]
	ds_write_b128 v9, v[0:3]
	v_lshl_add_u32 v0, v8, 6, v240
	ds_write_b128 v0, v[4:7] offset:49280
	v_add_u32_e32 v0, s4, v235
	v_add_u32_e32 v1, 0xfffffe80, v0
	v_cmp_lt_i32_e32 vcc, s23, v0
	s_and_b64 s[18:19], s[48:49], s[46:47]
	s_waitcnt vmcnt(5)
	v_cndmask_b32_e64 v3, v141, 0, s[18:19]
	v_cndmask_b32_e32 v8, v0, v1, vcc
	v_cndmask_b32_e64 v2, v140, 0, s[18:19]
	v_cndmask_b32_e64 v1, v139, 0, s[18:19]
	v_cndmask_b32_e64 v0, v138, 0, s[18:19]
	v_lshl_add_u32 v9, v8, 4, v239
	v_mov_b32_e32 v225, 0x1fcf
	s_waitcnt vmcnt(4)
	v_cndmask_b32_e64 v7, v145, 0, s[18:19]
	v_cndmask_b32_e64 v6, v144, 0, s[18:19]
	v_cndmask_b32_e64 v5, v143, 0, s[18:19]
	v_cndmask_b32_e64 v4, v142, 0, s[18:19]
	ds_write_b128 v9, v[0:3]
	v_lshl_add_u32 v0, v8, 6, v240
	s_andn2_b64 vcc, exec, s[24:25]
	ds_write_b128 v0, v[4:7] offset:49280
	s_cbranch_vccnz .LBB0_106
	v_add_u32_e32 v0, s4, v236
	v_readlane_b32 s18, v255, 17
	v_add_u32_e32 v1, 0xfffffe80, v0
	v_cmp_lt_i32_e32 vcc, s23, v0
	v_readlane_b32 s19, v255, 18
	s_and_b64 s[18:19], s[46:47], s[18:19]
	v_cndmask_b32_e32 v8, v0, v1, vcc
	v_lshl_add_u32 v9, v8, 4, v239
	v_cndmask_b32_e64 v3, v121, 0, s[18:19]
	v_cndmask_b32_e64 v2, v120, 0, s[18:19]
	v_cndmask_b32_e64 v1, v119, 0, s[18:19]
	v_cndmask_b32_e64 v0, v118, 0, s[18:19]
	v_cndmask_b32_e64 v7, v125, 0, s[18:19]
	v_cndmask_b32_e64 v6, v124, 0, s[18:19]
	v_cndmask_b32_e64 v5, v123, 0, s[18:19]
	v_cndmask_b32_e64 v4, v122, 0, s[18:19]
	ds_write_b128 v9, v[0:3]
	v_lshl_add_u32 v0, v8, 6, v240
	ds_write_b128 v0, v[4:7] offset:49280
	v_add_u32_e32 v0, s4, v237
	v_readlane_b32 s18, v255, 40
	v_add_u32_e32 v1, 0xfffffe80, v0
	v_cmp_lt_i32_e32 vcc, s23, v0
	v_readlane_b32 s19, v255, 41
	s_and_b64 s[18:19], s[46:47], s[18:19]
	v_cndmask_b32_e32 v8, v0, v1, vcc
	v_lshl_add_u32 v9, v8, 4, v239
	v_cndmask_b32_e64 v3, v133, 0, s[18:19]
	v_cndmask_b32_e64 v2, v132, 0, s[18:19]
	v_cndmask_b32_e64 v1, v131, 0, s[18:19]
	v_cndmask_b32_e64 v0, v130, 0, s[18:19]
	v_cndmask_b32_e64 v7, v137, 0, s[18:19]
	v_cndmask_b32_e64 v6, v136, 0, s[18:19]
	v_cndmask_b32_e64 v5, v135, 0, s[18:19]
	v_cndmask_b32_e64 v4, v134, 0, s[18:19]
	ds_write_b128 v9, v[0:3]
	v_lshl_add_u32 v0, v8, 6, v240
	ds_write_b128 v0, v[4:7] offset:49280
